# prompt attention even half-step: softmax fma/exp block and half of the row-sum chain spread under the QK^T MFMAs (temporaries renamed to free registers; only ops reading soon-overwritten registers sta
# baseline (speedup 1.0000x reference)
; __device__ __forceinline__ void partialSM(f32x16& p0, f32x16& p1, float& m_reg, float& mn, float& alpha) {
;     ...
;     const float mnL = -mn * C2;
;     for (int r = 0; r < 16; ++r) p0[r] = fmaf(p0[r], C2, mnL); for (int r = 0; r < 16; ++r) p1[r] = fmaf(p1[r], C2, mnL);
;     for (int r = 0; r < 16; ++r) p0[r] = __builtin_amdgcn_exp2f(p0[r]);
.LBB0_1253:
	s_waitcnt lgkmcnt(0)
	s_barrier
	v_cndmask_b32_e64 v247, v0, v180, s[4:5]
	v_mul_f32_e32 v0, 0xbe0293ee, v247
	v_fmamk_f32 v210, v112, 0x3e0293ee, v0
	v_fmamk_f32 v211, v113, 0x3e0293ee, v0
	v_fmamk_f32 v212, v114, 0x3e0293ee, v0
	v_fmamk_f32 v213, v115, 0x3e0293ee, v0
	v_fmamk_f32 v197, v96, 0x3e0293ee, v0
	v_fmamk_f32 v181, v97, 0x3e0293ee, v0
	v_fmamk_f32 v182, v98, 0x3e0293ee, v0
	v_fmamk_f32 v196, v99, 0x3e0293ee, v0
	s_add_i32 s4, s61, 1
	s_cmp_lt_i32 s4, s59
	s_cselect_b64 s[28:29], -1, 0
	s_cmp_ge_i32 s4, s59
	s_cbranch_scc1 .Lattn_h2_noload
	v_add_u32_e32 v200, 0x41, v248
	v_lshl_add_u64 v[2:3], v[200:201], 2, s[66:67]
	v_add_u32_e32 v200, 0x20000, v14
	v_lshlrev_b64 v[10:11], 1, v[200:201]
	v_add_u32_e32 v200, 0x30000, v14
	v_lshlrev_b64 v[12:13], 1, v[200:201]
	global_load_dword v246, v[2:3], off
	v_lshl_add_u64 v[2:3], s[64:65], 0, v[10:11]
	v_lshl_add_u64 v[6:7], s[64:65], 0, v[12:13]
	v_lshl_add_u64 v[10:11], s[62:63], 0, v[10:11]
	v_lshl_add_u64 v[176:177], s[62:63], 0, v[12:13]
	global_load_dwordx4 v[2:5], v[2:3], off
	s_nop 0
	global_load_dwordx4 v[6:9], v[6:7], off
	s_nop 0
	global_load_dwordx4 v[10:13], v[10:11], off
	s_nop 0
	global_load_dwordx4 v[176:179], v[176:177], off
; __device__ __forceinline__ void partialSM(f32x16& p0, f32x16& p1, float& m_reg, float& mn, float& alpha) {
;     ...
;     const float mnL = -mn * C2;
;     for (int r = 0; r < 16; ++r) p0[r] = fmaf(p0[r], C2, mnL); for (int r = 0; r < 16; ++r) p1[r] = fmaf(p1[r], C2, mnL);
;     for (int r = 0; r < 16; ++r) p0[r] = __builtin_amdgcn_exp2f(p0[r]);
; }
; __device__ __forceinline__ void finishSM(f32x16& p0, f32x16& p1, float alpha, float& l_reg, bf16x8& pa0, bf16x8& pa1, bf16x8& pa2, bf16x8& pa3) {
;     for (int r = 0; r < 16; ++r) p1[r] = __builtin_amdgcn_exp2f(p1[r]);
;     float ps = 0; for (int r = 0; r < 16; ++r) ps += p0[r]; for (int r = 0; r < 16; ++r) ps += p1[r];
;     { auto rr = __builtin_amdgcn_permlane32_swap(__float_as_uint(ps), __float_as_uint(ps), false, false);
;       ps = __uint_as_float(rr[0]) + __uint_as_float(rr[1]); }
;     l_reg = l_reg * alpha + ps;
;     ...
;     PK4(p0, 0, pa0); PK4(p0, 8, pa1); PK4(p1, 0, pa2); PK4(p1, 8, pa3);
;     ...
; }
; template <int KB, bool SK>
; __device__ __forceinline__ void qkt(f32x16& p0, f32x16& p1, const char* K_lds, const float* B_lds, int r32, int hi, const bf16x8* qr, bool act) {
;     if (SK && !act) { const float NEG = -__builtin_inff();
; #pragma unroll
;         for (int r = 0; r < 16; ++r) { p0[r] = NEG; p1[r] = NEG; } return; }
;     ...
;     p0 = f32x16{}; p1 = f32x16{};
;     ...
;     p0 = *(const f32x16*)(B_lds + KB * 64 + hi * 32); p1 = *(const f32x16*)(B_lds + KB * 64 + hi * 32 + 16);
;     ...
;     const char* kb[4];
; #pragma unroll
;     for (int dd = 0; dd < 4; ++dd) kb[dd] = K_lds + KB * SHM_K + KSWZ(r32, (dd * 16 + hi * 8) * 2);
; #pragma unroll
;     for (int d0 = 0; d0 < 8; ++d0) { const char* a = kb[d0 & 3] + (d0 >> 2) * 128;
;         bf16x8 b0 = *reinterpret_cast<const bf16x8*>(a);
;         bf16x8 b1 = *reinterpret_cast<const bf16x8*>(a + 32 * 256);
;         p0 = __builtin_amdgcn_mfma_f32_32x32x16_bf16(b0, qr[d0], p0, 0, 0, 0);
;         p1 = __builtin_amdgcn_mfma_f32_32x32x16_bf16(b1, qr[d0], p1, 0, 0, 0); }
; }
.Lattn_h2_noload:
	ds_read_b128 v[128:131], v239
	ds_read_b128 v[132:135], v239 offset:16
	ds_read_b128 v[136:139], v239 offset:32
	ds_read_b128 v[140:143], v239 offset:48
	ds_read_b128 v[124:127], v239 offset:112
	ds_read_b128 v[120:123], v239 offset:96
	ds_read_b128 v[116:119], v239 offset:80
	ds_read_b128 v[112:115], v239 offset:64
	ds_read_b128 v[96:99], v235 offset:32768
	ds_read_b128 v[184:187], v235 offset:40960
	s_waitcnt lgkmcnt(1)
	v_mfma_f32_32x32x16_bf16 v[128:143], v[96:99], v[172:175], v[128:143]
	v_fmamk_f32 v80, v100, 0x3e0293ee, v0
	v_fmamk_f32 v81, v101, 0x3e0293ee, v0
	v_fmamk_f32 v82, v102, 0x3e0293ee, v0
	v_fmamk_f32 v83, v103, 0x3e0293ee, v0
	v_fmamk_f32 v202, v104, 0x3e0293ee, v0
	s_waitcnt lgkmcnt(0)
	v_mfma_f32_32x32x16_bf16 v[112:127], v[184:187], v[172:175], v[112:127]
	ds_read_b128 v[96:99], v234 offset:32768
	ds_read_b128 v[184:187], v234 offset:40960
	v_fmamk_f32 v203, v105, 0x3e0293ee, v0
	v_fmamk_f32 v204, v106, 0x3e0293ee, v0
	v_fmamk_f32 v205, v107, 0x3e0293ee, v0
	v_fmamk_f32 v206, v108, 0x3e0293ee, v0
	v_fmamk_f32 v207, v109, 0x3e0293ee, v0
	s_waitcnt lgkmcnt(1)
	v_mfma_f32_32x32x16_bf16 v[128:143], v[96:99], v[168:171], v[128:143]
	v_fmamk_f32 v208, v110, 0x3e0293ee, v0
	v_fmamk_f32 v209, v111, 0x3e0293ee, v0
	v_fmamk_f32 v100, v84, 0x3e0293ee, v0
	v_fmamk_f32 v109, v85, 0x3e0293ee, v0
	v_fmamk_f32 v110, v86, 0x3e0293ee, v0
	s_waitcnt lgkmcnt(0)
	v_mfma_f32_32x32x16_bf16 v[112:127], v[184:187], v[168:171], v[112:127]
	ds_read_b128 v[96:99], v233 offset:32768
	ds_read_b128 v[184:187], v233 offset:40960
	v_fmamk_f32 v111, v87, 0x3e0293ee, v0
	v_fmamk_f32 v180, v88, 0x3e0293ee, v0
	v_fmamk_f32 v101, v89, 0x3e0293ee, v0
	v_fmamk_f32 v102, v90, 0x3e0293ee, v0
	v_fmamk_f32 v103, v91, 0x3e0293ee, v0
	s_waitcnt lgkmcnt(1)
	v_mfma_f32_32x32x16_bf16 v[128:143], v[96:99], v[164:167], v[128:143]
	v_fmamk_f32 v104, v92, 0x3e0293ee, v0
	v_fmamk_f32 v105, v93, 0x3e0293ee, v0
	v_fmamk_f32 v106, v94, 0x3e0293ee, v0
	v_fmamk_f32 v107, v95, 0x3e0293ee, v0
	v_exp_f32_e32 v80, v80
	s_waitcnt lgkmcnt(0)
	v_mfma_f32_32x32x16_bf16 v[112:127], v[184:187], v[164:167], v[112:127]
	ds_read_b128 v[96:99], v232 offset:32768
	ds_read_b128 v[184:187], v232 offset:40960
	v_exp_f32_e32 v81, v81
	v_exp_f32_e32 v82, v82
	v_exp_f32_e32 v83, v83
	v_exp_f32_e32 v84, v202
	v_exp_f32_e32 v85, v203
	s_waitcnt lgkmcnt(1)
	v_mfma_f32_32x32x16_bf16 v[128:143], v[96:99], v[160:163], v[128:143]
	v_exp_f32_e32 v86, v204
	v_exp_f32_e32 v87, v205
	v_exp_f32_e32 v88, v206
	v_exp_f32_e32 v89, v207
	v_exp_f32_e32 v90, v208
	s_waitcnt lgkmcnt(0)
	v_mfma_f32_32x32x16_bf16 v[112:127], v[184:187], v[160:163], v[112:127]
	ds_read_b128 v[96:99], v235 offset:32896
	ds_read_b128 v[184:187], v235 offset:41088
	v_exp_f32_e32 v91, v209
	v_exp_f32_e32 v92, v210
	v_exp_f32_e32 v93, v211
	v_exp_f32_e32 v94, v212
	v_exp_f32_e32 v95, v213
	s_waitcnt lgkmcnt(1)
	v_mfma_f32_32x32x16_bf16 v[128:143], v[96:99], v[156:159], v[128:143]
	v_exp_f32_e32 v101, v101
	v_exp_f32_e32 v102, v102
	v_exp_f32_e32 v103, v103
	v_exp_f32_e32 v104, v104
	s_waitcnt lgkmcnt(0)
	v_mfma_f32_32x32x16_bf16 v[112:127], v[184:187], v[156:159], v[112:127]
	ds_read_b128 v[96:99], v234 offset:32896
	ds_read_b128 v[184:187], v234 offset:41088
	v_exp_f32_e32 v105, v105
	v_exp_f32_e32 v106, v106
	v_exp_f32_e32 v107, v107
	v_exp_f32_e32 v108, v197
	s_waitcnt lgkmcnt(1)
	v_mfma_f32_32x32x16_bf16 v[128:143], v[96:99], v[152:155], v[128:143]
	v_add_f32_e32 v0, 0, v80
	v_add_f32_e32 v0, v81, v0
	v_add_f32_e32 v0, v82, v0
	v_add_f32_e32 v0, v83, v0
	s_waitcnt lgkmcnt(0)
	v_mfma_f32_32x32x16_bf16 v[112:127], v[184:187], v[152:155], v[112:127]
	ds_read_b128 v[96:99], v233 offset:32896
	ds_read_b128 v[184:187], v233 offset:41088
	v_add_f32_e32 v0, v84, v0
	v_add_f32_e32 v0, v85, v0
	v_add_f32_e32 v0, v86, v0
	v_add_f32_e32 v0, v87, v0
	s_waitcnt lgkmcnt(1)
	v_mfma_f32_32x32x16_bf16 v[128:143], v[96:99], v[148:151], v[128:143]
	v_add_f32_e32 v0, v88, v0
	v_add_f32_e32 v0, v89, v0
	v_add_f32_e32 v0, v90, v0
	v_add_f32_e32 v0, v91, v0
	s_waitcnt lgkmcnt(0)
	v_mfma_f32_32x32x16_bf16 v[112:127], v[184:187], v[148:151], v[112:127]
	ds_read_b128 v[96:99], v232 offset:32896
	ds_read_b128 v[184:187], v232 offset:41088
	v_add_f32_e32 v0, v92, v0
	v_add_f32_e32 v0, v93, v0
	v_add_f32_e32 v0, v94, v0
	v_add_f32_e32 v0, v95, v0
	s_waitcnt lgkmcnt(1)
	v_mfma_f32_32x32x16_bf16 v[128:143], v[96:99], v[144:147], v[128:143]
	v_exp_f32_e32 v99, v111
	v_exp_f32_e32 v111, v196
	v_exp_f32_e32 v96, v100
	v_exp_f32_e32 v97, v109
	v_exp_f32_e32 v98, v110
	v_exp_f32_e32 v100, v180
	v_add_f32_e32 v0, v96, v0
	v_add_f32_e32 v0, v97, v0
	v_add_f32_e32 v0, v98, v0
	v_add_f32_e32 v0, v99, v0
	v_add_f32_e32 v0, v100, v0
	v_add_f32_e32 v0, v101, v0
	v_add_f32_e32 v0, v102, v0
	v_add_f32_e32 v0, v103, v0
	v_add_f32_e32 v0, v104, v0
	v_exp_f32_e32 v109, v181
	v_add_f32_e32 v0, v105, v0
	s_waitcnt lgkmcnt(0)
	v_mfma_f32_32x32x16_bf16 v[112:127], v[184:187], v[144:147], v[112:127]
	v_exp_f32_e32 v110, v182
	v_add_f32_e32 v0, v106, v0
	v_add_f32_e32 v0, v107, v0
	v_add_f32_e32 v0, v108, v0
	v_add_f32_e32 v0, v109, v0
	v_add_f32_e32 v0, v110, v0
	v_add_f32_e32 v249, v111, v0
	v_mov_b32_e32 v250, v249
	v_cvt_pk_bf16_f32 v180, v80, v81
	v_cvt_pk_bf16_f32 v181, v82, v83
	v_cvt_pk_bf16_f32 v182, v84, v85
	v_cvt_pk_bf16_f32 v183, v86, v87
	v_cvt_pk_bf16_f32 v184, v88, v89
	v_cvt_pk_bf16_f32 v185, v90, v91
	v_cvt_pk_bf16_f32 v186, v92, v93
	v_cvt_pk_bf16_f32 v187, v94, v95
	v_cvt_pk_bf16_f32 v188, v96, v97
	v_cvt_pk_bf16_f32 v189, v98, v99
	v_cvt_pk_bf16_f32 v190, v100, v101
	v_cvt_pk_bf16_f32 v191, v102, v103
	v_cvt_pk_bf16_f32 v192, v104, v105
	v_cvt_pk_bf16_f32 v193, v106, v107
	v_cvt_pk_bf16_f32 v194, v108, v109
	v_cvt_pk_bf16_f32 v195, v110, v111
	s_nop 1
	v_permlane32_swap_b32_e32 v249, v250
	v_permlane32_swap_b32_e32 v180, v182
	v_permlane32_swap_b32_e32 v181, v183
	v_permlane32_swap_b32_e32 v184, v186
	v_permlane32_swap_b32_e32 v185, v187
	v_permlane32_swap_b32_e32 v188, v190
	v_permlane32_swap_b32_e32 v189, v191
	v_permlane32_swap_b32_e32 v192, v194
	v_permlane32_swap_b32_e32 v193, v195
